# EpiGU reformulated: silu(g*rs)*(u*rs) = g*u / ((1+exp2(g*rs*-log2e)) * (mean+eps)); 16 packed f32 ops per row instead of 24, same exp/rcp count
# speedup vs baseline: 1.0045x; 1.0045x over previous
.LBB0_82:
	s_lshl_b32 s0, s54, 8
	s_add_i32 s0, s0, s65
	s_lshl_b32 s26, s53, 7
	v_and_or_b32 v140, v218, 15, s0
	v_ashrrev_i32_e32 v141, 31, v140
	v_lshl_add_u64 v[142:143], v[140:141], 3, s[10:11]
	global_load_dwordx2 v[146:147], v[142:143], off
	global_load_dwordx2 v[148:149], v[142:143], off offset:128
	global_load_dwordx2 v[150:151], v[142:143], off offset:256
	global_load_dwordx2 v[152:153], v[142:143], off offset:384
	global_load_dwordx2 v[154:155], v[142:143], off offset:1024
	global_load_dwordx2 v[156:157], v[142:143], off offset:1152
	global_load_dwordx2 v[158:159], v[142:143], off offset:1280
	global_load_dwordx2 v[160:161], v[142:143], off offset:1408
	s_ashr_i32 s27, s26, 31
	s_movk_i32 s13, 0x1600
	s_lshl_b64 s[26:27], s[26:27], 1
	v_and_b32_e32 v184, 48, v218
	s_andn2_b64 vcc, exec, s[4:5]
	v_mov_b64_e32 v[196:197], s[90:91]
	v_mad_i64_i32 v[190:191], s[0:1], v140, s13, v[196:197]
	v_lshl_add_u64 v[190:191], v[190:191], 0, s[26:27]
	v_lshl_add_u64 v[190:191], v[190:191], 0, s[88:89]
	v_lshl_add_u64 v[190:191], v[190:191], 0, v[184:185]
	v_mov_b32_e32 v178, 0xbfb8aa3b
	v_mov_b32_e32 v180, 1.0
	s_waitcnt vmcnt(0)
	v_ffbh_u32_e32 v162, v147
	v_ffbh_u32_e32 v164, v149
	v_ffbh_u32_e32 v166, v151
	v_ffbh_u32_e32 v168, v153
	v_ffbh_u32_e32 v170, v155
	v_ffbh_u32_e32 v172, v157
	v_ffbh_u32_e32 v174, v159
	v_ffbh_u32_e32 v176, v161
	v_min_u32_e32 v162, 32, v162
	v_min_u32_e32 v164, 32, v164
	v_min_u32_e32 v166, 32, v166
	v_min_u32_e32 v168, 32, v168
	v_min_u32_e32 v170, 32, v170
	v_min_u32_e32 v172, 32, v172
	v_min_u32_e32 v174, 32, v174
	v_min_u32_e32 v176, 32, v176
	v_lshlrev_b64 v[146:147], v162, v[146:147]
	v_lshlrev_b64 v[148:149], v164, v[148:149]
	v_lshlrev_b64 v[150:151], v166, v[150:151]
	v_lshlrev_b64 v[152:153], v168, v[152:153]
	v_lshlrev_b64 v[154:155], v170, v[154:155]
	v_lshlrev_b64 v[156:157], v172, v[156:157]
	v_lshlrev_b64 v[158:159], v174, v[158:159]
	v_lshlrev_b64 v[160:161], v176, v[160:161]
	v_min_u32_e32 v146, 1, v146
	v_min_u32_e32 v148, 1, v148
	v_min_u32_e32 v150, 1, v150
	v_min_u32_e32 v152, 1, v152
	v_min_u32_e32 v154, 1, v154
	v_min_u32_e32 v156, 1, v156
	v_min_u32_e32 v158, 1, v158
	v_min_u32_e32 v160, 1, v160
	v_or_b32_e32 v146, v147, v146
	v_or_b32_e32 v148, v149, v148
	v_or_b32_e32 v150, v151, v150
	v_or_b32_e32 v152, v153, v152
	v_or_b32_e32 v154, v155, v154
	v_or_b32_e32 v156, v157, v156
	v_or_b32_e32 v158, v159, v158
	v_or_b32_e32 v160, v161, v160
	v_cvt_f32_u32_e32 v146, v146
	v_cvt_f32_u32_e32 v148, v148
	v_cvt_f32_u32_e32 v150, v150
	v_cvt_f32_u32_e32 v152, v152
	v_cvt_f32_u32_e32 v154, v154
	v_cvt_f32_u32_e32 v156, v156
	v_cvt_f32_u32_e32 v158, v158
	v_cvt_f32_u32_e32 v160, v160
	v_sub_u32_e32 v162, 32, v162
	v_sub_u32_e32 v164, 32, v164
	v_sub_u32_e32 v166, 32, v166
	v_sub_u32_e32 v168, 32, v168
	v_sub_u32_e32 v170, 32, v170
	v_sub_u32_e32 v172, 32, v172
	v_sub_u32_e32 v174, 32, v174
	v_sub_u32_e32 v176, 32, v176
	v_ldexp_f32 v162, v146, v162
	v_ldexp_f32 v164, v148, v164
	v_ldexp_f32 v166, v150, v166
	v_ldexp_f32 v168, v152, v168
	v_ldexp_f32 v170, v154, v170
	v_ldexp_f32 v172, v156, v172
	v_ldexp_f32 v174, v158, v174
	v_ldexp_f32 v176, v160, v176
	v_mul_f32_e32 v162, 0x33800000, v162
	v_mul_f32_e32 v164, 0x33800000, v164
	v_mul_f32_e32 v166, 0x33800000, v166
	v_mul_f32_e32 v168, 0x33800000, v168
	v_mul_f32_e32 v170, 0x33800000, v170
	v_mul_f32_e32 v172, 0x33800000, v172
	v_mul_f32_e32 v174, 0x33800000, v174
	v_mul_f32_e32 v176, 0x33800000, v176
	v_fmamk_f32 v162, v162, 0x3a800000, v219
	v_fmamk_f32 v164, v164, 0x3a800000, v219
	v_fmamk_f32 v166, v166, 0x3a800000, v219
	v_fmamk_f32 v168, v168, 0x3a800000, v219
	v_fmamk_f32 v170, v170, 0x3a800000, v219
	v_fmamk_f32 v172, v172, 0x3a800000, v219
	v_fmamk_f32 v174, v174, 0x3a800000, v219
	v_fmamk_f32 v176, v176, 0x3a800000, v219
	v_rsq_f32_e32 v236, v162
	v_rsq_f32_e32 v238, v164
	v_rsq_f32_e32 v240, v166
	v_rsq_f32_e32 v242, v168
	v_rsq_f32_e32 v244, v170
	v_rsq_f32_e32 v246, v172
	v_rsq_f32_e32 v248, v174
	v_rsq_f32_e32 v250, v176
	v_mul_f32_e32 v236, 0xbfb8aa3b, v236
	v_mul_f32_e32 v238, 0xbfb8aa3b, v238
	v_mul_f32_e32 v240, 0xbfb8aa3b, v240
	v_mul_f32_e32 v242, 0xbfb8aa3b, v242
	v_mul_f32_e32 v244, 0xbfb8aa3b, v244
	v_mul_f32_e32 v246, 0xbfb8aa3b, v246
	v_mul_f32_e32 v248, 0xbfb8aa3b, v248
	v_mul_f32_e32 v250, 0xbfb8aa3b, v250
	v_pk_mul_f32 v[146:147], v[124:125], v[236:237] op_sel_hi:[1,0]
	v_pk_mul_f32 v[148:149], v[126:127], v[236:237] op_sel_hi:[1,0]
	v_pk_mul_f32 v[150:151], v[116:117], v[236:237] op_sel_hi:[1,0]
	v_pk_mul_f32 v[152:153], v[118:119], v[236:237] op_sel_hi:[1,0]
	v_exp_f32_e32 v146, v146
	v_exp_f32_e32 v147, v147
	v_exp_f32_e32 v148, v148
	v_exp_f32_e32 v149, v149
	v_exp_f32_e32 v150, v150
	v_exp_f32_e32 v151, v151
	v_exp_f32_e32 v152, v152
	v_exp_f32_e32 v153, v153
	v_pk_mul_f32 v[120:121], v[124:125], v[120:121]
	v_pk_mul_f32 v[122:123], v[126:127], v[122:123]
	v_pk_mul_f32 v[112:113], v[116:117], v[112:113]
	v_pk_mul_f32 v[114:115], v[118:119], v[114:115]
	v_pk_fma_f32 v[146:147], v[146:147], v[162:163], v[162:163] op_sel_hi:[1,0,0]
	v_pk_fma_f32 v[148:149], v[148:149], v[162:163], v[162:163] op_sel_hi:[1,0,0]
	v_pk_fma_f32 v[150:151], v[150:151], v[162:163], v[162:163] op_sel_hi:[1,0,0]
	v_pk_fma_f32 v[152:153], v[152:153], v[162:163], v[162:163] op_sel_hi:[1,0,0]
	v_rcp_f32_e32 v146, v146
	v_rcp_f32_e32 v147, v147
	v_rcp_f32_e32 v148, v148
	v_rcp_f32_e32 v149, v149
	v_rcp_f32_e32 v150, v150
	v_rcp_f32_e32 v151, v151
	v_rcp_f32_e32 v152, v152
	v_rcp_f32_e32 v153, v153
	v_pk_mul_f32 v[124:125], v[120:121], v[146:147]
	v_pk_mul_f32 v[126:127], v[122:123], v[148:149]
	v_pk_mul_f32 v[116:117], v[112:113], v[150:151]
	v_pk_mul_f32 v[118:119], v[114:115], v[152:153]
	v_cvt_pk_bf16_f32 v202, v124, v125
	v_cvt_pk_bf16_f32 v203, v126, v127
	v_cvt_pk_bf16_f32 v204, v116, v117
	v_cvt_pk_bf16_f32 v205, v118, v119
	global_store_dwordx4 v[190:191], v[202:205], off
	s_mov_b64 s[0:1], 0x16000
	v_lshl_add_u64 v[194:195], v[190:191], 0, s[0:1]
	v_pk_mul_f32 v[146:147], v[108:109], v[238:239] op_sel_hi:[1,0]
	v_pk_mul_f32 v[148:149], v[110:111], v[238:239] op_sel_hi:[1,0]
	v_pk_mul_f32 v[150:151], v[100:101], v[238:239] op_sel_hi:[1,0]
	v_pk_mul_f32 v[152:153], v[102:103], v[238:239] op_sel_hi:[1,0]
	v_exp_f32_e32 v146, v146
	v_exp_f32_e32 v147, v147
	v_exp_f32_e32 v148, v148
	v_exp_f32_e32 v149, v149
	v_exp_f32_e32 v150, v150
	v_exp_f32_e32 v151, v151
	v_exp_f32_e32 v152, v152
	v_exp_f32_e32 v153, v153
	v_pk_mul_f32 v[104:105], v[108:109], v[104:105]
	v_pk_mul_f32 v[106:107], v[110:111], v[106:107]
	v_pk_mul_f32 v[96:97], v[100:101], v[96:97]
	v_pk_mul_f32 v[98:99], v[102:103], v[98:99]
	v_pk_fma_f32 v[146:147], v[146:147], v[164:165], v[164:165] op_sel_hi:[1,0,0]
	v_pk_fma_f32 v[148:149], v[148:149], v[164:165], v[164:165] op_sel_hi:[1,0,0]
	v_pk_fma_f32 v[150:151], v[150:151], v[164:165], v[164:165] op_sel_hi:[1,0,0]
	v_pk_fma_f32 v[152:153], v[152:153], v[164:165], v[164:165] op_sel_hi:[1,0,0]
	v_rcp_f32_e32 v146, v146
	v_rcp_f32_e32 v147, v147
	v_rcp_f32_e32 v148, v148
	v_rcp_f32_e32 v149, v149
	v_rcp_f32_e32 v150, v150
	v_rcp_f32_e32 v151, v151
	v_rcp_f32_e32 v152, v152
	v_rcp_f32_e32 v153, v153
	v_pk_mul_f32 v[108:109], v[104:105], v[146:147]
	v_pk_mul_f32 v[110:111], v[106:107], v[148:149]
	v_pk_mul_f32 v[100:101], v[96:97], v[150:151]
	v_pk_mul_f32 v[102:103], v[98:99], v[152:153]
	v_cvt_pk_bf16_f32 v206, v108, v109
	v_cvt_pk_bf16_f32 v207, v110, v111
	v_cvt_pk_bf16_f32 v208, v100, v101
	v_cvt_pk_bf16_f32 v209, v102, v103
	global_store_dwordx4 v[194:195], v[206:209], off
	s_mov_b64 s[0:1], 0x2c000
	v_lshl_add_u64 v[192:193], v[190:191], 0, s[0:1]
	v_pk_mul_f32 v[146:147], v[92:93], v[240:241] op_sel_hi:[1,0]
	v_pk_mul_f32 v[148:149], v[94:95], v[240:241] op_sel_hi:[1,0]
	v_pk_mul_f32 v[150:151], v[84:85], v[240:241] op_sel_hi:[1,0]
	v_pk_mul_f32 v[152:153], v[86:87], v[240:241] op_sel_hi:[1,0]
	v_exp_f32_e32 v146, v146
	v_exp_f32_e32 v147, v147
	v_exp_f32_e32 v148, v148
	v_exp_f32_e32 v149, v149
	v_exp_f32_e32 v150, v150
	v_exp_f32_e32 v151, v151
	v_exp_f32_e32 v152, v152
	v_exp_f32_e32 v153, v153
	v_pk_mul_f32 v[88:89], v[92:93], v[88:89]
	v_pk_mul_f32 v[90:91], v[94:95], v[90:91]
	v_pk_mul_f32 v[80:81], v[84:85], v[80:81]
	v_pk_mul_f32 v[82:83], v[86:87], v[82:83]
	v_pk_fma_f32 v[146:147], v[146:147], v[166:167], v[166:167] op_sel_hi:[1,0,0]
	v_pk_fma_f32 v[148:149], v[148:149], v[166:167], v[166:167] op_sel_hi:[1,0,0]
	v_pk_fma_f32 v[150:151], v[150:151], v[166:167], v[166:167] op_sel_hi:[1,0,0]
	v_pk_fma_f32 v[152:153], v[152:153], v[166:167], v[166:167] op_sel_hi:[1,0,0]
	v_rcp_f32_e32 v146, v146
	v_rcp_f32_e32 v147, v147
	v_rcp_f32_e32 v148, v148
	v_rcp_f32_e32 v149, v149
	v_rcp_f32_e32 v150, v150
	v_rcp_f32_e32 v151, v151
	v_rcp_f32_e32 v152, v152
	v_rcp_f32_e32 v153, v153
	v_pk_mul_f32 v[92:93], v[88:89], v[146:147]
	v_pk_mul_f32 v[94:95], v[90:91], v[148:149]
	v_pk_mul_f32 v[84:85], v[80:81], v[150:151]
	v_pk_mul_f32 v[86:87], v[82:83], v[152:153]
	v_cvt_pk_bf16_f32 v210, v92, v93
	v_cvt_pk_bf16_f32 v211, v94, v95
	v_cvt_pk_bf16_f32 v212, v84, v85
	v_cvt_pk_bf16_f32 v213, v86, v87
	global_store_dwordx4 v[192:193], v[210:213], off
	s_mov_b64 s[0:1], 0x42000
	v_lshl_add_u64 v[194:195], v[190:191], 0, s[0:1]
	v_pk_mul_f32 v[146:147], v[76:77], v[242:243] op_sel_hi:[1,0]
	v_pk_mul_f32 v[148:149], v[78:79], v[242:243] op_sel_hi:[1,0]
	v_pk_mul_f32 v[150:151], v[68:69], v[242:243] op_sel_hi:[1,0]
	v_pk_mul_f32 v[152:153], v[70:71], v[242:243] op_sel_hi:[1,0]
	v_exp_f32_e32 v146, v146
	v_exp_f32_e32 v147, v147
	v_exp_f32_e32 v148, v148
	v_exp_f32_e32 v149, v149
	v_exp_f32_e32 v150, v150
	v_exp_f32_e32 v151, v151
	v_exp_f32_e32 v152, v152
	v_exp_f32_e32 v153, v153
	v_pk_mul_f32 v[72:73], v[76:77], v[72:73]
	v_pk_mul_f32 v[74:75], v[78:79], v[74:75]
	v_pk_mul_f32 v[64:65], v[68:69], v[64:65]
	v_pk_mul_f32 v[66:67], v[70:71], v[66:67]
	v_pk_fma_f32 v[146:147], v[146:147], v[168:169], v[168:169] op_sel_hi:[1,0,0]
	v_pk_fma_f32 v[148:149], v[148:149], v[168:169], v[168:169] op_sel_hi:[1,0,0]
	v_pk_fma_f32 v[150:151], v[150:151], v[168:169], v[168:169] op_sel_hi:[1,0,0]
	v_pk_fma_f32 v[152:153], v[152:153], v[168:169], v[168:169] op_sel_hi:[1,0,0]
	v_rcp_f32_e32 v146, v146
	v_rcp_f32_e32 v147, v147
	v_rcp_f32_e32 v148, v148
	v_rcp_f32_e32 v149, v149
	v_rcp_f32_e32 v150, v150
	v_rcp_f32_e32 v151, v151
	v_rcp_f32_e32 v152, v152
	v_rcp_f32_e32 v153, v153
	v_pk_mul_f32 v[76:77], v[72:73], v[146:147]
	v_pk_mul_f32 v[78:79], v[74:75], v[148:149]
	v_pk_mul_f32 v[68:69], v[64:65], v[150:151]
	v_pk_mul_f32 v[70:71], v[66:67], v[152:153]
	v_cvt_pk_bf16_f32 v214, v76, v77
	v_cvt_pk_bf16_f32 v215, v78, v79
	v_cvt_pk_bf16_f32 v216, v68, v69
	v_cvt_pk_bf16_f32 v217, v70, v71
	global_store_dwordx4 v[194:195], v[214:217], off
	s_mov_b64 s[0:1], 0xb0000
	v_lshl_add_u64 v[192:193], v[190:191], 0, s[0:1]
	v_pk_mul_f32 v[146:147], v[60:61], v[244:245] op_sel_hi:[1,0]
	v_pk_mul_f32 v[148:149], v[62:63], v[244:245] op_sel_hi:[1,0]
	v_pk_mul_f32 v[150:151], v[52:53], v[244:245] op_sel_hi:[1,0]
	v_pk_mul_f32 v[152:153], v[54:55], v[244:245] op_sel_hi:[1,0]
	v_exp_f32_e32 v146, v146
	v_exp_f32_e32 v147, v147
	v_exp_f32_e32 v148, v148
	v_exp_f32_e32 v149, v149
	v_exp_f32_e32 v150, v150
	v_exp_f32_e32 v151, v151
	v_exp_f32_e32 v152, v152
	v_exp_f32_e32 v153, v153
	v_pk_mul_f32 v[56:57], v[60:61], v[56:57]
	v_pk_mul_f32 v[58:59], v[62:63], v[58:59]
	v_pk_mul_f32 v[48:49], v[52:53], v[48:49]
	v_pk_mul_f32 v[50:51], v[54:55], v[50:51]
	v_pk_fma_f32 v[146:147], v[146:147], v[170:171], v[170:171] op_sel_hi:[1,0,0]
	v_pk_fma_f32 v[148:149], v[148:149], v[170:171], v[170:171] op_sel_hi:[1,0,0]
	v_pk_fma_f32 v[150:151], v[150:151], v[170:171], v[170:171] op_sel_hi:[1,0,0]
	v_pk_fma_f32 v[152:153], v[152:153], v[170:171], v[170:171] op_sel_hi:[1,0,0]
	v_rcp_f32_e32 v146, v146
	v_rcp_f32_e32 v147, v147
	v_rcp_f32_e32 v148, v148
	v_rcp_f32_e32 v149, v149
	v_rcp_f32_e32 v150, v150
	v_rcp_f32_e32 v151, v151
	v_rcp_f32_e32 v152, v152
	v_rcp_f32_e32 v153, v153
	v_pk_mul_f32 v[60:61], v[56:57], v[146:147]
	v_pk_mul_f32 v[62:63], v[58:59], v[148:149]
	v_pk_mul_f32 v[52:53], v[48:49], v[150:151]
	v_pk_mul_f32 v[54:55], v[50:51], v[152:153]
	v_cvt_pk_bf16_f32 v202, v60, v61
	v_cvt_pk_bf16_f32 v203, v62, v63
	v_cvt_pk_bf16_f32 v204, v52, v53
	v_cvt_pk_bf16_f32 v205, v54, v55
	global_store_dwordx4 v[192:193], v[202:205], off
	s_mov_b64 s[0:1], 0xc6000
	v_lshl_add_u64 v[194:195], v[190:191], 0, s[0:1]
	v_pk_mul_f32 v[146:147], v[44:45], v[246:247] op_sel_hi:[1,0]
	v_pk_mul_f32 v[148:149], v[46:47], v[246:247] op_sel_hi:[1,0]
	v_pk_mul_f32 v[150:151], v[36:37], v[246:247] op_sel_hi:[1,0]
	v_pk_mul_f32 v[152:153], v[38:39], v[246:247] op_sel_hi:[1,0]
	v_exp_f32_e32 v146, v146
	v_exp_f32_e32 v147, v147
	v_exp_f32_e32 v148, v148
	v_exp_f32_e32 v149, v149
	v_exp_f32_e32 v150, v150
	v_exp_f32_e32 v151, v151
	v_exp_f32_e32 v152, v152
	v_exp_f32_e32 v153, v153
	v_pk_mul_f32 v[40:41], v[44:45], v[40:41]
	v_pk_mul_f32 v[42:43], v[46:47], v[42:43]
	v_pk_mul_f32 v[32:33], v[36:37], v[32:33]
	v_pk_mul_f32 v[34:35], v[38:39], v[34:35]
	v_pk_fma_f32 v[146:147], v[146:147], v[172:173], v[172:173] op_sel_hi:[1,0,0]
	v_pk_fma_f32 v[148:149], v[148:149], v[172:173], v[172:173] op_sel_hi:[1,0,0]
	v_pk_fma_f32 v[150:151], v[150:151], v[172:173], v[172:173] op_sel_hi:[1,0,0]
	v_pk_fma_f32 v[152:153], v[152:153], v[172:173], v[172:173] op_sel_hi:[1,0,0]
	v_rcp_f32_e32 v146, v146
	v_rcp_f32_e32 v147, v147
	v_rcp_f32_e32 v148, v148
	v_rcp_f32_e32 v149, v149
	v_rcp_f32_e32 v150, v150
	v_rcp_f32_e32 v151, v151
	v_rcp_f32_e32 v152, v152
	v_rcp_f32_e32 v153, v153
	v_pk_mul_f32 v[44:45], v[40:41], v[146:147]
	v_pk_mul_f32 v[46:47], v[42:43], v[148:149]
	v_pk_mul_f32 v[36:37], v[32:33], v[150:151]
	v_pk_mul_f32 v[38:39], v[34:35], v[152:153]
	v_cvt_pk_bf16_f32 v206, v44, v45
	v_cvt_pk_bf16_f32 v207, v46, v47
	v_cvt_pk_bf16_f32 v208, v36, v37
	v_cvt_pk_bf16_f32 v209, v38, v39
	global_store_dwordx4 v[194:195], v[206:209], off
	s_mov_b64 s[0:1], 0xdc000
	v_lshl_add_u64 v[192:193], v[190:191], 0, s[0:1]
	v_pk_mul_f32 v[146:147], v[28:29], v[248:249] op_sel_hi:[1,0]
	v_pk_mul_f32 v[148:149], v[30:31], v[248:249] op_sel_hi:[1,0]
	v_pk_mul_f32 v[150:151], v[20:21], v[248:249] op_sel_hi:[1,0]
	v_pk_mul_f32 v[152:153], v[22:23], v[248:249] op_sel_hi:[1,0]
	v_exp_f32_e32 v146, v146
	v_exp_f32_e32 v147, v147
	v_exp_f32_e32 v148, v148
	v_exp_f32_e32 v149, v149
	v_exp_f32_e32 v150, v150
	v_exp_f32_e32 v151, v151
	v_exp_f32_e32 v152, v152
	v_exp_f32_e32 v153, v153
	v_pk_mul_f32 v[24:25], v[28:29], v[24:25]
	v_pk_mul_f32 v[26:27], v[30:31], v[26:27]
	v_pk_mul_f32 v[16:17], v[20:21], v[16:17]
	v_pk_mul_f32 v[18:19], v[22:23], v[18:19]
	v_pk_fma_f32 v[146:147], v[146:147], v[174:175], v[174:175] op_sel_hi:[1,0,0]
	v_pk_fma_f32 v[148:149], v[148:149], v[174:175], v[174:175] op_sel_hi:[1,0,0]
	v_pk_fma_f32 v[150:151], v[150:151], v[174:175], v[174:175] op_sel_hi:[1,0,0]
	v_pk_fma_f32 v[152:153], v[152:153], v[174:175], v[174:175] op_sel_hi:[1,0,0]
	v_rcp_f32_e32 v146, v146
	v_rcp_f32_e32 v147, v147
	v_rcp_f32_e32 v148, v148
	v_rcp_f32_e32 v149, v149
	v_rcp_f32_e32 v150, v150
	v_rcp_f32_e32 v151, v151
	v_rcp_f32_e32 v152, v152
	v_rcp_f32_e32 v153, v153
	v_pk_mul_f32 v[28:29], v[24:25], v[146:147]
	v_pk_mul_f32 v[30:31], v[26:27], v[148:149]
	v_pk_mul_f32 v[20:21], v[16:17], v[150:151]
	v_pk_mul_f32 v[22:23], v[18:19], v[152:153]
	v_cvt_pk_bf16_f32 v210, v28, v29
	v_cvt_pk_bf16_f32 v211, v30, v31
	v_cvt_pk_bf16_f32 v212, v20, v21
	v_cvt_pk_bf16_f32 v213, v22, v23
	global_store_dwordx4 v[192:193], v[210:213], off
	s_mov_b64 s[0:1], 0xf2000
	v_lshl_add_u64 v[194:195], v[190:191], 0, s[0:1]
	v_pk_mul_f32 v[146:147], v[12:13], v[250:251] op_sel_hi:[1,0]
	v_pk_mul_f32 v[148:149], v[14:15], v[250:251] op_sel_hi:[1,0]
	v_pk_mul_f32 v[150:151], v[4:5], v[250:251] op_sel_hi:[1,0]
	v_pk_mul_f32 v[152:153], v[6:7], v[250:251] op_sel_hi:[1,0]
	v_exp_f32_e32 v146, v146
	v_exp_f32_e32 v147, v147
	v_exp_f32_e32 v148, v148
	v_exp_f32_e32 v149, v149
	v_exp_f32_e32 v150, v150
	v_exp_f32_e32 v151, v151
	v_exp_f32_e32 v152, v152
	v_exp_f32_e32 v153, v153
	v_pk_mul_f32 v[8:9], v[12:13], v[8:9]
	v_pk_mul_f32 v[10:11], v[14:15], v[10:11]
	v_pk_mul_f32 v[0:1], v[4:5], v[0:1]
	v_pk_mul_f32 v[2:3], v[6:7], v[2:3]
	v_pk_fma_f32 v[146:147], v[146:147], v[176:177], v[176:177] op_sel_hi:[1,0,0]
	v_pk_fma_f32 v[148:149], v[148:149], v[176:177], v[176:177] op_sel_hi:[1,0,0]
	v_pk_fma_f32 v[150:151], v[150:151], v[176:177], v[176:177] op_sel_hi:[1,0,0]
	v_pk_fma_f32 v[152:153], v[152:153], v[176:177], v[176:177] op_sel_hi:[1,0,0]
	v_rcp_f32_e32 v146, v146
	v_rcp_f32_e32 v147, v147
	v_rcp_f32_e32 v148, v148
	v_rcp_f32_e32 v149, v149
	v_rcp_f32_e32 v150, v150
	v_rcp_f32_e32 v151, v151
	v_rcp_f32_e32 v152, v152
	v_rcp_f32_e32 v153, v153
	v_pk_mul_f32 v[12:13], v[8:9], v[146:147]
	v_pk_mul_f32 v[14:15], v[10:11], v[148:149]
	v_pk_mul_f32 v[4:5], v[0:1], v[150:151]
	v_pk_mul_f32 v[6:7], v[2:3], v[152:153]
	v_cvt_pk_bf16_f32 v214, v12, v13
	v_cvt_pk_bf16_f32 v215, v14, v15
	v_cvt_pk_bf16_f32 v216, v4, v5
	v_cvt_pk_bf16_f32 v217, v6, v7
	global_store_dwordx4 v[194:195], v[214:217], off
	s_mov_b64 s[0:1], -1
	s_cbranch_vccnz .LBB0_75
	s_andn2_b64 vcc, exec, s[2:3]
	s_cbranch_vccnz .LBB0_74
	s_barrier
	s_branch .LBB0_74
